# cross-attention QK k-loop fully unrolled: immediate LDS offsets, no per-iteration address adds/branch, first iteration takes the score init as SrcC (16 v_mov_b64 per tile removed)
# speedup vs baseline: 1.0074x; 1.0074x over previous
; #define LAS __attribute__((address_space(3)))
; template <bool DIFF> ...
;     ...
;             f32x16 s0 = biasv, s1 = biasv;
;             LAS const unsigned char* ka = kb + l32 * KSTR + (DIFF ? c * 128 : 0) + hi * 16;
; #pragma unroll 1
;             for (int kq = 0; kq < NKS; kq += 4) {
;                 bf16x8 ka0[4], ka1[4], qq[4];
; #pragma unroll
;                 for (int j = 0; j < 4; ++j) {
;                     if (DIFF) { const int ko = 256 * l32 + 16 * (((c << 3) + 2 * j + hi) ^ (((l32 & 3) << 2) | ((l32 >> 2) & 3)));
;                         ka0[j] = *(LAS const bf16x8*)(kb + ko); ka1[j] = *(LAS const bf16x8*)(kb + 8192 + ko); }
;                     else { ka0[j] = *(LAS const bf16x8*)(ka + (kq + j) * 32); ka1[j] = *(LAS const bf16x8*)(ka + 32 * KSTR + (kq + j) * 32); }
;                     qq[j] = DIFF ? qf[DIFF ? j : 0] : *(LAS const bf16x8*)(qa + (kq + j) * 32); }
;                 __builtin_amdgcn_sched_barrier(0);
; #pragma unroll
;                 for (int j = 0; j < 4; ++j) { s0 = __builtin_amdgcn_mfma_f32_32x32x16_bf16(ka0[j], qq[j], s0, 0, 0, 0); s1 = __builtin_amdgcn_mfma_f32_32x32x16_bf16(ka1[j], qq[j], s1, 0, 0, 0); }
;             }
.LBB0_255:
	v_add_u32_e32 v147, v201, v200
	v_add_u32_e32 v176, v206, v200
	v_add_u32_e32 v237, 0x11400, v176
	s_waitcnt lgkmcnt(0)
	s_barrier
	ds_read_b128 v[164:167], v237
	ds_read_b128 v[148:151], v147
	ds_read_b128 v[156:159], v147 offset:16896
	ds_read_b128 v[168:171], v237 offset:32
	ds_read_b128 v[152:155], v147 offset:32
	ds_read_b128 v[160:163], v147 offset:16928
	ds_read_b128 v[222:225], v237 offset:64
	ds_read_b128 v[172:175], v147 offset:64
	ds_read_b128 v[214:217], v147 offset:16960
	ds_read_b128 v[226:229], v237 offset:96
	ds_read_b128 v[210:213], v147 offset:96
	ds_read_b128 v[218:221], v147 offset:16992
	s_waitcnt lgkmcnt(9)
	v_mfma_f32_32x32x16_bf16 v[98:113], v[148:151], v[164:167], v[66:81]
	v_mfma_f32_32x32x16_bf16 v[82:97], v[156:159], v[164:167], v[66:81]
	s_waitcnt lgkmcnt(6)
	v_mfma_f32_32x32x16_bf16 v[98:113], v[152:155], v[168:171], v[98:113]
	v_mfma_f32_32x32x16_bf16 v[82:97], v[160:163], v[168:171], v[82:97]
	s_waitcnt lgkmcnt(3)
	v_mfma_f32_32x32x16_bf16 v[98:113], v[172:175], v[222:225], v[98:113]
	v_mfma_f32_32x32x16_bf16 v[82:97], v[214:217], v[222:225], v[82:97]
	s_waitcnt lgkmcnt(0)
	v_mfma_f32_32x32x16_bf16 v[98:113], v[210:213], v[226:229], v[98:113]
	v_mfma_f32_32x32x16_bf16 v[82:97], v[218:221], v[226:229], v[82:97]
	ds_read_b128 v[164:167], v237 offset:128
	ds_read_b128 v[148:151], v147 offset:128
	ds_read_b128 v[156:159], v147 offset:17024
	ds_read_b128 v[168:171], v237 offset:160
	ds_read_b128 v[152:155], v147 offset:160
	ds_read_b128 v[160:163], v147 offset:17056
	ds_read_b128 v[222:225], v237 offset:192
	ds_read_b128 v[172:175], v147 offset:192
	ds_read_b128 v[214:217], v147 offset:17088
	ds_read_b128 v[226:229], v237 offset:224
	ds_read_b128 v[210:213], v147 offset:224
	ds_read_b128 v[218:221], v147 offset:17120
	s_waitcnt lgkmcnt(9)
	v_mfma_f32_32x32x16_bf16 v[98:113], v[148:151], v[164:167], v[98:113]
	v_mfma_f32_32x32x16_bf16 v[82:97], v[156:159], v[164:167], v[82:97]
	s_waitcnt lgkmcnt(6)
	v_mfma_f32_32x32x16_bf16 v[98:113], v[152:155], v[168:171], v[98:113]
	v_mfma_f32_32x32x16_bf16 v[82:97], v[160:163], v[168:171], v[82:97]
	s_waitcnt lgkmcnt(3)
	v_mfma_f32_32x32x16_bf16 v[98:113], v[172:175], v[222:225], v[98:113]
	v_mfma_f32_32x32x16_bf16 v[82:97], v[214:217], v[222:225], v[82:97]
	s_waitcnt lgkmcnt(0)
	v_mfma_f32_32x32x16_bf16 v[98:113], v[210:213], v[226:229], v[98:113]
	v_mfma_f32_32x32x16_bf16 v[82:97], v[218:221], v[226:229], v[82:97]
	ds_read_b128 v[164:167], v237 offset:256
	ds_read_b128 v[148:151], v147 offset:256
	ds_read_b128 v[156:159], v147 offset:17152
	ds_read_b128 v[168:171], v237 offset:288
	ds_read_b128 v[152:155], v147 offset:288
	ds_read_b128 v[160:163], v147 offset:17184
	ds_read_b128 v[222:225], v237 offset:320
	ds_read_b128 v[172:175], v147 offset:320
	ds_read_b128 v[214:217], v147 offset:17216
	ds_read_b128 v[226:229], v237 offset:352
	ds_read_b128 v[210:213], v147 offset:352
	ds_read_b128 v[218:221], v147 offset:17248
	s_waitcnt lgkmcnt(9)
	v_mfma_f32_32x32x16_bf16 v[98:113], v[148:151], v[164:167], v[98:113]
	v_mfma_f32_32x32x16_bf16 v[82:97], v[156:159], v[164:167], v[82:97]
	s_waitcnt lgkmcnt(6)
	v_mfma_f32_32x32x16_bf16 v[98:113], v[152:155], v[168:171], v[98:113]
	v_mfma_f32_32x32x16_bf16 v[82:97], v[160:163], v[168:171], v[82:97]
	s_waitcnt lgkmcnt(3)
	v_mfma_f32_32x32x16_bf16 v[98:113], v[172:175], v[222:225], v[98:113]
	v_mfma_f32_32x32x16_bf16 v[82:97], v[214:217], v[222:225], v[82:97]
	s_waitcnt lgkmcnt(0)
	v_mfma_f32_32x32x16_bf16 v[98:113], v[210:213], v[226:229], v[98:113]
	v_mfma_f32_32x32x16_bf16 v[82:97], v[218:221], v[226:229], v[82:97]
	ds_read_b128 v[164:167], v237 offset:384
	ds_read_b128 v[148:151], v147 offset:384
	ds_read_b128 v[156:159], v147 offset:17280
	ds_read_b128 v[168:171], v237 offset:416
	ds_read_b128 v[152:155], v147 offset:416
	ds_read_b128 v[160:163], v147 offset:17312
	ds_read_b128 v[222:225], v237 offset:448
	ds_read_b128 v[172:175], v147 offset:448
	ds_read_b128 v[214:217], v147 offset:17344
	ds_read_b128 v[226:229], v237 offset:480
	ds_read_b128 v[210:213], v147 offset:480
	ds_read_b128 v[218:221], v147 offset:17376
	s_waitcnt lgkmcnt(9)
	v_mfma_f32_32x32x16_bf16 v[98:113], v[148:151], v[164:167], v[98:113]
	v_mfma_f32_32x32x16_bf16 v[82:97], v[156:159], v[164:167], v[82:97]
	s_waitcnt lgkmcnt(6)
	v_mfma_f32_32x32x16_bf16 v[98:113], v[152:155], v[168:171], v[98:113]
	v_mfma_f32_32x32x16_bf16 v[82:97], v[160:163], v[168:171], v[82:97]
	s_waitcnt lgkmcnt(3)
	v_mfma_f32_32x32x16_bf16 v[98:113], v[172:175], v[222:225], v[98:113]
	v_mfma_f32_32x32x16_bf16 v[82:97], v[214:217], v[222:225], v[82:97]
	s_waitcnt lgkmcnt(0)
	v_mfma_f32_32x32x16_bf16 v[98:113], v[210:213], v[226:229], v[98:113]
	v_mfma_f32_32x32x16_bf16 v[82:97], v[218:221], v[226:229], v[82:97]
	ds_read_b64_tr_b16 v[162:163], v204 offset:33792
	ds_read_b64_tr_b16 v[164:165], v204 offset:38400
	ds_read_b64_tr_b16 v[148:149], v204 offset:38464
	ds_read_b64_tr_b16 v[146:147], v204 offset:33856
	ds_read_b64_tr_b16 v[166:167], v204 offset:43008
	ds_read_b64_tr_b16 v[168:169], v204 offset:47616
	ds_read_b64_tr_b16 v[152:153], v204 offset:47680
	ds_read_b64_tr_b16 v[150:151], v204 offset:43072
	ds_read_b64_tr_b16 v[170:171], v204 offset:52224
	ds_read_b64_tr_b16 v[172:173], v204 offset:56832
	ds_read_b64_tr_b16 v[156:157], v204 offset:56896
	ds_read_b64_tr_b16 v[154:155], v204 offset:52288
	ds_read_b64_tr_b16 v[174:175], v204 offset:61440
	ds_read_b64_tr_b16 v[176:177], v205 offset:32256
	ds_read_b64_tr_b16 v[160:161], v205 offset:32320
	ds_read_b64_tr_b16 v[158:159], v204 offset:61504
	v_max3_f32 v0, v98, v99, v100
	v_max3_f32 v236, v82, v83, v84
	v_max3_f32 v0, v0, v101, v102
	v_max3_f32 v236, v236, v85, v86
	v_max3_f32 v0, v0, v103, v104
	v_max3_f32 v236, v236, v87, v88
	v_max3_f32 v0, v0, v105, v106
	v_max3_f32 v236, v236, v89, v90
	v_max3_f32 v0, v0, v107, v108
	v_max3_f32 v236, v236, v91, v92
	v_max3_f32 v0, v0, v109, v110
	v_max3_f32 v236, v236, v93, v94
	v_max3_f32 v0, v0, v111, v112
	v_max3_f32 v236, v236, v95, v96
	v_max_f32_e32 v0, v0, v113
	v_max_f32_e32 v236, v236, v97
	v_fma_f32 v0, v0, s44, 0
	v_fma_f32 v236, v236, s44, 0
	v_max_f32_e32 v0, v0, v236
	v_mov_b32_e32 v209, v0
	v_mov_b32_e32 v236, v0
	s_nop 1
	v_permlane32_swap_b32_e32 v209, v236
	s_nop 1
	v_max_f32_e32 v0, v209, v236
	s_waitcnt lgkmcnt(14)
	v_cmp_gt_f32_e32 vcc, v0, v208
	s_cbranch_vccz .LBB0_252
; template <bool DIFF> ...
;     ...
;             if (__builtin_amdgcn_ballot_w64(mx > m_run) != 0ull) {
;                 const float mnew = fmaxf(m_run, mx), alpha = __builtin_amdgcn_exp2f(m_run - mnew); m_run = mnew; l_run *= alpha;
; #pragma unroll
;                 for (int i = 0; i < 4; ++i)
; #pragma unroll
;                     for (int r = 0; r < 16; ++r) o[i][r] *= alpha;
;             }
	v_max_f32_e32 v0, v0, v0
	v_max_f32_e32 v209, v208, v208
	v_max_f32_e32 v209, v209, v0
	v_sub_f32_e32 v0, v208, v209
	v_exp_f32_e32 v0, v0
	v_mov_b32_e32 v208, v209
	v_pk_mul_f32 v[64:65], v[64:65], v[0:1] op_sel_hi:[1,0]
	v_pk_mul_f32 v[62:63], v[62:63], v[0:1] op_sel_hi:[1,0]
	v_pk_mul_f32 v[60:61], v[60:61], v[0:1] op_sel_hi:[1,0]
	v_pk_mul_f32 v[58:59], v[58:59], v[0:1] op_sel_hi:[1,0]
	v_pk_mul_f32 v[56:57], v[56:57], v[0:1] op_sel_hi:[1,0]
	v_pk_mul_f32 v[54:55], v[54:55], v[0:1] op_sel_hi:[1,0]
	v_pk_mul_f32 v[52:53], v[52:53], v[0:1] op_sel_hi:[1,0]
	v_pk_mul_f32 v[50:51], v[50:51], v[0:1] op_sel_hi:[1,0]
	v_pk_mul_f32 v[48:49], v[48:49], v[0:1] op_sel_hi:[1,0]
	v_pk_mul_f32 v[46:47], v[46:47], v[0:1] op_sel_hi:[1,0]
	v_pk_mul_f32 v[44:45], v[44:45], v[0:1] op_sel_hi:[1,0]
	v_pk_mul_f32 v[42:43], v[42:43], v[0:1] op_sel_hi:[1,0]
	v_pk_mul_f32 v[40:41], v[40:41], v[0:1] op_sel_hi:[1,0]
	v_pk_mul_f32 v[38:39], v[38:39], v[0:1] op_sel_hi:[1,0]
	v_pk_mul_f32 v[36:37], v[36:37], v[0:1] op_sel_hi:[1,0]
	v_pk_mul_f32 v[34:35], v[34:35], v[0:1] op_sel_hi:[1,0]
	v_pk_mul_f32 v[32:33], v[32:33], v[0:1] op_sel_hi:[1,0]
	v_pk_mul_f32 v[30:31], v[30:31], v[0:1] op_sel_hi:[1,0]
	v_pk_mul_f32 v[28:29], v[28:29], v[0:1] op_sel_hi:[1,0]
	v_pk_mul_f32 v[26:27], v[26:27], v[0:1] op_sel_hi:[1,0]
	v_pk_mul_f32 v[24:25], v[24:25], v[0:1] op_sel_hi:[1,0]
	v_pk_mul_f32 v[22:23], v[22:23], v[0:1] op_sel_hi:[1,0]
	v_pk_mul_f32 v[20:21], v[20:21], v[0:1] op_sel_hi:[1,0]
	v_pk_mul_f32 v[18:19], v[18:19], v[0:1] op_sel_hi:[1,0]
	v_pk_mul_f32 v[16:17], v[16:17], v[0:1] op_sel_hi:[1,0]
	v_pk_mul_f32 v[14:15], v[14:15], v[0:1] op_sel_hi:[1,0]
	v_pk_mul_f32 v[12:13], v[12:13], v[0:1] op_sel_hi:[1,0]
	v_pk_mul_f32 v[10:11], v[10:11], v[0:1] op_sel_hi:[1,0]
	v_pk_mul_f32 v[8:9], v[8:9], v[0:1] op_sel_hi:[1,0]
	v_pk_mul_f32 v[6:7], v[6:7], v[0:1] op_sel_hi:[1,0]
	v_pk_mul_f32 v[4:5], v[4:5], v[0:1] op_sel_hi:[1,0]
	v_pk_mul_f32 v[2:3], v[2:3], v[0:1] op_sel_hi:[1,0]
	v_mul_f32_e32 v203, v203, v0
	s_branch .LBB0_252
